# acc-switch LDS latency hidden: lgkm wait moved from unit top to before the switch
# speedup vs baseline: 1.0102x; 1.0102x over previous
.Lxp_ixqd:
	s_mov_b32 s25, 0
	s_waitcnt vmcnt(10) lgkmcnt(0)
.Lxp_unit:
	s_cmp_eq_u32 s82, 1
	s_cbranch_scc0 .Lxp_fola
	s_lshl_b32 s2, s25, 7
	s_add_i32 s2, s2, s97
	s_and_b32 s2, s2, 0x3fff
	v_mov_b32_e32 v245, s2
	s_mov_b64 exec, 1
	global_store_dword v[246:247], v245, off
	s_mov_b64 exec, -1
	s_sleep 3
	s_branch .Lxp_syncda
.Lxp_fola:
	v_readfirstlane_b32 s2, v132
	s_mov_b32 vcc_lo, 16
	s_and_b32 s83, s84, 0x3fff

.Lxp_syncda:
	s_and_b32 s84, s84, 0x3fff
	s_lshl_b32 s2, s84, 11
	v_lshl_add_u32 v249, v60, 4, s2
	global_load_dwordx4 v[72:75], v249, s[18:19]
	global_load_dwordx4 v[64:67], v249, s[20:21]
	s_lshl_b32 s2, s84, 2
	v_writelane_b32 v147, s2, 0
	v_writelane_b32 v2, s85, 0
	s_and_b32 s86, s86, 0x3fff
	s_lshl_b32 s2, s86, 11
	v_lshl_add_u32 v249, v60, 4, s2
	global_load_dwordx4 v[76:79], v249, s[18:19]
	global_load_dwordx4 v[68:71], v249, s[20:21]
	s_lshl_b32 s2, s86, 2
	v_writelane_b32 v147, s2, 1
	v_writelane_b32 v2, s87, 1
	s_and_b32 s88, s88, 0x3fff
	s_lshl_b32 s2, s88, 11
	v_lshl_add_u32 v249, v60, 4, s2
	global_load_dwordx4 v[80:83], v249, s[18:19]
	global_load_dwordx4 v[4:7], v249, s[20:21]
	s_lshl_b32 s2, s88, 2
	v_writelane_b32 v147, s2, 2
	v_writelane_b32 v2, s89, 2
	s_and_b32 s90, s90, 0x3fff
	s_lshl_b32 s2, s90, 11
	v_lshl_add_u32 v249, v60, 4, s2
	global_load_dwordx4 v[84:87], v249, s[18:19]
	global_load_dwordx4 v[128:131], v249, s[20:21]
	s_lshl_b32 s2, s90, 2
	v_writelane_b32 v147, s2, 3
	v_writelane_b32 v2, s91, 3
	global_load_dword v88, v147, s[44:45]
	global_load_dword v89, v147, s[46:47]
	s_add_i32 s3, s25, 3
	s_min_u32 s3, s3, 0x7f
	s_cmp_lt_u32 s3, 64
	s_cselect_b64 vcc, -1, 0
	s_nop 0
	v_cndmask_b32_e32 v249, v241, v240, vcc
	s_nop 1
	v_readlane_b32 s2, v249, s3
	s_and_b32 s3, s2, 31
	s_lshl_b32 s3, s3, 5
	s_bfe_u32 s94, s2, 0x20005
	s_lshl_b32 s2, s94, 11
	s_add_i32 s3, s3, s2
	s_load_dwordx8 s[84:91], s[36:37], s3
	v_mov_b32_e32 v149, 0
	v_mov_b32_e32 v150, 0
	v_mov_b32_e32 v151, 0
	v_mov_b32_e32 v148, 0
	v_dot4c_i32_i8_e32 v149, v8, v133
	v_dot4c_i32_i8_e32 v150, v16, v133
	v_dot4c_i32_i8_e32 v151, v32, v133
	v_dot4c_i32_i8_e32 v148, v36, v133
	v_dot4c_i32_i8_e32 v149, v9, v134
	v_dot4c_i32_i8_e32 v150, v17, v134
	v_dot4c_i32_i8_e32 v151, v33, v134
	v_dot4c_i32_i8_e32 v148, v37, v134
	v_dot4c_i32_i8_e32 v149, v10, v135
	v_dot4c_i32_i8_e32 v150, v18, v135
	v_dot4c_i32_i8_e32 v151, v34, v135
	v_dot4c_i32_i8_e32 v148, v38, v135
	v_dot4c_i32_i8_e32 v149, v11, v136
	v_dot4c_i32_i8_e32 v150, v19, v136
	v_dot4c_i32_i8_e32 v151, v35, v136
	v_dot4c_i32_i8_e32 v148, v39, v136
	s_nop 3
	v_cndmask_b32_e64 v143, v149, v150, s[0:1]
	v_cndmask_b32_e64 v144, v150, v149, s[0:1]
	v_cndmask_b32_e64 v145, v151, v148, s[0:1]
	v_cndmask_b32_e64 v146, v148, v151, s[0:1]
	s_nop 1
	v_add_u32_dpp v144, v143, v144 quad_perm:[1,0,3,2] row_mask:0xf bank_mask:0xf
	v_add_u32_dpp v146, v145, v146 quad_perm:[1,0,3,2] row_mask:0xf bank_mask:0xf
	s_nop 1
	v_cndmask_b32_e64 v143, v144, v146, s[6:7]
	v_cndmask_b32_e64 v145, v146, v144, s[6:7]
	s_nop 1
	v_add_u32_dpp v145, v143, v145 quad_perm:[2,3,0,1] row_mask:0xf bank_mask:0xf
	s_nop 1
	v_add_u32_dpp v145, v145, v145 row_ror:4 row_mask:0xf bank_mask:0xf
	s_nop 1
	v_add_u32_dpp v145, v145, v145 row_ror:8 row_mask:0xf bank_mask:0xf
	s_nop 1
	ds_bpermute_b32 v143, v126, v145
	s_waitcnt lgkmcnt(0)
	v_add_u32_e32 v145, v145, v143
	ds_bpermute_b32 v143, v127, v145
	s_waitcnt lgkmcnt(0)
	v_add_u32_e32 v145, v145, v143
	v_cvt_f32_i32_e32 v56, v145
	v_mul_f32_e32 v59, v138, v56
	v_mul_f32_e32 v59, v137, v59
	v_mul_f32_e32 v56, 0x3f3504f3, v59
	v_fma_f32 v143, |v56|, s66, v120
	v_fma_f32 v143, |v56|, v143, s67
	v_fma_f32 v143, |v56|, v143, s68
	v_fma_f32 v143, |v56|, v143, s69
	v_fma_f32 v143, |v56|, v143, s70
	v_fma_f32 v143, |v56|, v143, s71
	v_fma_f32 v143, |v56|, v143, |v56|
	v_mul_f32_e32 v144, 0xbfb8aa3b, v143
	v_fma_f32 v146, v143, s72, -v144
	v_rndne_f32_e32 v3, v144
	v_fmac_f32_e32 v146, 0xb2a5705f, v143
	v_sub_f32_e32 v144, v144, v3
	v_add_f32_e32 v144, v144, v146
	v_cvt_i32_f32_e32 v146, v3
	v_exp_f32_e32 v144, v144
	v_cmp_nlt_f32_e32 vcc, s73, v143
	v_ldexp_f32 v144, v144, v146
	s_nop 0
	v_cndmask_b32_e32 v144, 0, v144, vcc
	v_cmp_ngt_f32_e32 vcc, s74, v143
	s_nop 1
	v_cndmask_b32_e32 v143, v121, v144, vcc
	v_sub_f32_e32 v143, 1.0, v143
	v_mul_f32_e32 v168, v56, v56
	v_fmamk_f32 v169, v168, 0xba1345e1, v117
	v_fmaak_f32 v169, v168, v169, 0xbcdac9b8
	v_fmaak_f32 v169, v168, v169, 0x3de703be
	v_fmaak_f32 v169, v168, v169, 0xbec09330
	v_fmaak_f32 v168, v168, v169, 0x3e0375d0
	v_fma_f32 v168, |v56|, v168, |v56|
	v_cmp_nlt_f32_e64 vcc, |v56|, 1.0
	s_nop 1
	v_cndmask_b32_e32 v143, v168, v143, vcc
	v_bfi_b32 v146, s75, v143, v56
	v_mul_f32_e32 v145, 0.5, v59
	v_add_f32_e32 v146, 1.0, v146
	v_mul_f32_e32 v145, v145, v146
	v_mul_f32_e32 v144, v0, v145
	v_mul_f32_e32 v143, v139, v144
	s_nop 1
	v_readlane_b32 s40, v143, 0
	v_readlane_b32 s38, v143, 1
	v_readlane_b32 s42, v143, 2
	v_readlane_b32 s2, v143, 3
	s_nop 1
	v_add_f32_e32 v142, s40, v142
	v_add_f32_e32 v142, s38, v142
	v_add_f32_e32 v142, s42, v142
	v_add_f32_e32 v142, s2, v142
	v_cvt_f32_ubyte1_e32 v169, v40
	v_cvt_f32_ubyte0_e32 v168, v40
	v_pk_fma_f32 v[104:105], s[40:41], v[168:169], v[104:105] op_sel_hi:[0,1,1]
	v_cvt_f32_ubyte1_e32 v171, v44
	v_cvt_f32_ubyte0_e32 v170, v44
	v_pk_fma_f32 v[104:105], s[38:39], v[170:171], v[104:105] op_sel_hi:[0,1,1]
	v_cvt_f32_ubyte1_e32 v169, v48
	v_cvt_f32_ubyte0_e32 v168, v48
	v_pk_fma_f32 v[104:105], s[42:43], v[168:169], v[104:105] op_sel_hi:[0,1,1]
	v_cvt_f32_ubyte1_e32 v171, v52
	v_cvt_f32_ubyte0_e32 v170, v52
	v_pk_fma_f32 v[104:105], s[2:3], v[170:171], v[104:105] op_sel_hi:[0,1,1]
	v_cvt_f32_ubyte3_e32 v169, v40
	v_cvt_f32_ubyte2_e32 v168, v40
	v_pk_fma_f32 v[102:103], s[40:41], v[168:169], v[102:103] op_sel_hi:[0,1,1]
	v_cvt_f32_ubyte3_e32 v171, v44
	v_cvt_f32_ubyte2_e32 v170, v44
	v_pk_fma_f32 v[102:103], s[38:39], v[170:171], v[102:103] op_sel_hi:[0,1,1]
	v_cvt_f32_ubyte3_e32 v169, v48
	v_cvt_f32_ubyte2_e32 v168, v48
	v_pk_fma_f32 v[102:103], s[42:43], v[168:169], v[102:103] op_sel_hi:[0,1,1]
	v_cvt_f32_ubyte3_e32 v171, v52
	v_cvt_f32_ubyte2_e32 v170, v52
	v_pk_fma_f32 v[102:103], s[2:3], v[170:171], v[102:103] op_sel_hi:[0,1,1]
	v_cvt_f32_ubyte1_e32 v169, v41
	v_cvt_f32_ubyte0_e32 v168, v41
	v_pk_fma_f32 v[98:99], s[40:41], v[168:169], v[98:99] op_sel_hi:[0,1,1]
	v_cvt_f32_ubyte1_e32 v171, v45
	v_cvt_f32_ubyte0_e32 v170, v45
	v_pk_fma_f32 v[98:99], s[38:39], v[170:171], v[98:99] op_sel_hi:[0,1,1]
	v_cvt_f32_ubyte1_e32 v169, v49
	v_cvt_f32_ubyte0_e32 v168, v49
	v_pk_fma_f32 v[98:99], s[42:43], v[168:169], v[98:99] op_sel_hi:[0,1,1]
	v_cvt_f32_ubyte1_e32 v171, v53
	v_cvt_f32_ubyte0_e32 v170, v53
	v_pk_fma_f32 v[98:99], s[2:3], v[170:171], v[98:99] op_sel_hi:[0,1,1]
	v_cvt_f32_ubyte3_e32 v169, v41
	v_cvt_f32_ubyte2_e32 v168, v41
	v_pk_fma_f32 v[100:101], s[40:41], v[168:169], v[100:101] op_sel_hi:[0,1,1]
	v_cvt_f32_ubyte3_e32 v171, v45
	v_cvt_f32_ubyte2_e32 v170, v45
	v_pk_fma_f32 v[100:101], s[38:39], v[170:171], v[100:101] op_sel_hi:[0,1,1]
	v_cvt_f32_ubyte3_e32 v169, v49
	v_cvt_f32_ubyte2_e32 v168, v49
	v_pk_fma_f32 v[100:101], s[42:43], v[168:169], v[100:101] op_sel_hi:[0,1,1]
	v_cvt_f32_ubyte3_e32 v171, v53
	v_cvt_f32_ubyte2_e32 v170, v53
	v_pk_fma_f32 v[100:101], s[2:3], v[170:171], v[100:101] op_sel_hi:[0,1,1]
	v_cvt_f32_ubyte1_e32 v169, v42
	v_cvt_f32_ubyte0_e32 v168, v42
	v_pk_fma_f32 v[94:95], s[40:41], v[168:169], v[94:95] op_sel_hi:[0,1,1]
	v_cvt_f32_ubyte1_e32 v171, v46
	v_cvt_f32_ubyte0_e32 v170, v46
	v_pk_fma_f32 v[94:95], s[38:39], v[170:171], v[94:95] op_sel_hi:[0,1,1]
	v_cvt_f32_ubyte1_e32 v169, v50
	v_cvt_f32_ubyte0_e32 v168, v50
	v_pk_fma_f32 v[94:95], s[42:43], v[168:169], v[94:95] op_sel_hi:[0,1,1]
	v_cvt_f32_ubyte1_e32 v171, v54
	v_cvt_f32_ubyte0_e32 v170, v54
	v_pk_fma_f32 v[94:95], s[2:3], v[170:171], v[94:95] op_sel_hi:[0,1,1]
	v_cvt_f32_ubyte3_e32 v169, v42
	v_cvt_f32_ubyte2_e32 v168, v42
	v_pk_fma_f32 v[96:97], s[40:41], v[168:169], v[96:97] op_sel_hi:[0,1,1]
	v_cvt_f32_ubyte3_e32 v171, v46
	v_cvt_f32_ubyte2_e32 v170, v46
	v_pk_fma_f32 v[96:97], s[38:39], v[170:171], v[96:97] op_sel_hi:[0,1,1]
	v_cvt_f32_ubyte3_e32 v169, v50
	v_cvt_f32_ubyte2_e32 v168, v50
	v_pk_fma_f32 v[96:97], s[42:43], v[168:169], v[96:97] op_sel_hi:[0,1,1]
	v_cvt_f32_ubyte3_e32 v171, v54
	v_cvt_f32_ubyte2_e32 v170, v54
	v_pk_fma_f32 v[96:97], s[2:3], v[170:171], v[96:97] op_sel_hi:[0,1,1]
	v_cvt_f32_ubyte1_e32 v169, v43
	v_cvt_f32_ubyte0_e32 v168, v43
	v_pk_fma_f32 v[90:91], s[40:41], v[168:169], v[90:91] op_sel_hi:[0,1,1]
	v_cvt_f32_ubyte1_e32 v171, v47
	v_cvt_f32_ubyte0_e32 v170, v47
	v_pk_fma_f32 v[90:91], s[38:39], v[170:171], v[90:91] op_sel_hi:[0,1,1]
	v_cvt_f32_ubyte1_e32 v169, v51
	v_cvt_f32_ubyte0_e32 v168, v51
	v_pk_fma_f32 v[90:91], s[42:43], v[168:169], v[90:91] op_sel_hi:[0,1,1]
	v_cvt_f32_ubyte1_e32 v171, v55
	v_cvt_f32_ubyte0_e32 v170, v55
	v_pk_fma_f32 v[90:91], s[2:3], v[170:171], v[90:91] op_sel_hi:[0,1,1]
	v_cvt_f32_ubyte3_e32 v169, v43
	v_cvt_f32_ubyte2_e32 v168, v43
	v_pk_fma_f32 v[92:93], s[40:41], v[168:169], v[92:93] op_sel_hi:[0,1,1]
	v_cvt_f32_ubyte3_e32 v171, v47
	v_cvt_f32_ubyte2_e32 v170, v47
	v_pk_fma_f32 v[92:93], s[38:39], v[170:171], v[92:93] op_sel_hi:[0,1,1]
	v_cvt_f32_ubyte3_e32 v169, v51
	v_cvt_f32_ubyte2_e32 v168, v51
	v_pk_fma_f32 v[92:93], s[42:43], v[168:169], v[92:93] op_sel_hi:[0,1,1]
	v_cvt_f32_ubyte3_e32 v171, v55
	v_cvt_f32_ubyte2_e32 v170, v55
	v_pk_fma_f32 v[92:93], s[2:3], v[170:171], v[92:93] op_sel_hi:[0,1,1]
	s_waitcnt vmcnt(10) lgkmcnt(0)
	s_cmp_eq_u32 s80, s33
	s_cbranch_scc1 .Lxp_noswa
	s_lshl_b32 s2, s33, 12
	v_add_u32_e32 v249, s2, v248
	ds_write_b128 v249, v[90:93]
	ds_write_b128 v249, v[94:97] offset:1024
	ds_write_b128 v249, v[98:101] offset:2048
	ds_write_b128 v249, v[102:105] offset:3072
	v_cmp_eq_u32_e32 vcc, s33, v60
	s_nop 1
	v_cndmask_b32_e32 v243, v243, v142, vcc
	s_lshl_b32 s2, s80, 12
	v_add_u32_e32 v249, s2, v248
	ds_read_b128 v[90:93], v249
	ds_read_b128 v[94:97], v249 offset:1024
	ds_read_b128 v[98:101], v249 offset:2048
	ds_read_b128 v[102:105], v249 offset:3072
	s_nop 0
	v_readlane_b32 s2, v243, s80
	v_readlane_b32 s3, v244, s80
	s_nop 1
	v_mov_b32_e32 v142, s2
	v_mov_b32_e32 v137, s3
	s_cmp_eq_u32 s80, 0
	s_cbranch_scc1 .Lxp_lxqa0
	s_cmp_eq_u32 s80, 1
	s_cbranch_scc1 .Lxp_lxqa1
	s_cmp_eq_u32 s80, 2
	s_cbranch_scc1 .Lxp_lxqa2
	v_mov_b32_e32 v133, v236
	v_mov_b32_e32 v134, v237
	v_mov_b32_e32 v135, v238
	v_mov_b32_e32 v136, v239
	s_branch .Lxp_lxqad

.Lxp_noswa:
	s_mov_b32 s80, s81
	s_mov_b32 s81, s94
	s_add_i32 s25, s25, 1
	s_cmp_eq_u32 s82, 1
	s_cbranch_scc0 .Lxp_folb
	s_lshl_b32 s2, s25, 7
	s_add_i32 s2, s2, s97
	s_and_b32 s2, s2, 0x3fff
	v_mov_b32_e32 v245, s2
	s_mov_b64 exec, 1
	global_store_dword v[246:247], v245, off
	s_mov_b64 exec, -1
	s_sleep 3
	s_branch .Lxp_syncdb

.Lxp_syncdb:
	s_and_b32 s84, s84, 0x3fff
	s_lshl_b32 s2, s84, 11
	v_lshl_add_u32 v249, v60, 4, s2
	global_load_dwordx4 v[8:11], v249, s[18:19]
	global_load_dwordx4 v[40:43], v249, s[20:21]
	s_lshl_b32 s2, s84, 2
	v_writelane_b32 v147, s2, 0
	v_writelane_b32 v0, s85, 0
	s_and_b32 s86, s86, 0x3fff
	s_lshl_b32 s2, s86, 11
	v_lshl_add_u32 v249, v60, 4, s2
	global_load_dwordx4 v[16:19], v249, s[18:19]
	global_load_dwordx4 v[44:47], v249, s[20:21]
	s_lshl_b32 s2, s86, 2
	v_writelane_b32 v147, s2, 1
	v_writelane_b32 v0, s87, 1
	s_and_b32 s88, s88, 0x3fff
	s_lshl_b32 s2, s88, 11
	v_lshl_add_u32 v249, v60, 4, s2
	global_load_dwordx4 v[32:35], v249, s[18:19]
	global_load_dwordx4 v[48:51], v249, s[20:21]
	s_lshl_b32 s2, s88, 2
	v_writelane_b32 v147, s2, 2
	v_writelane_b32 v0, s89, 2
	s_and_b32 s90, s90, 0x3fff
	s_lshl_b32 s2, s90, 11
	v_lshl_add_u32 v249, v60, 4, s2
	global_load_dwordx4 v[36:39], v249, s[18:19]
	global_load_dwordx4 v[52:55], v249, s[20:21]
	s_lshl_b32 s2, s90, 2
	v_writelane_b32 v147, s2, 3
	v_writelane_b32 v0, s91, 3
	global_load_dword v138, v147, s[44:45]
	global_load_dword v139, v147, s[46:47]
	s_add_i32 s3, s25, 3
	s_min_u32 s3, s3, 0x7f
	s_cmp_lt_u32 s3, 64
	s_cselect_b64 vcc, -1, 0
	s_nop 0
	v_cndmask_b32_e32 v249, v241, v240, vcc
	s_nop 1
	v_readlane_b32 s2, v249, s3
	s_and_b32 s3, s2, 31
	s_lshl_b32 s3, s3, 5
	s_bfe_u32 s94, s2, 0x20005
	s_lshl_b32 s2, s94, 11
	s_add_i32 s3, s3, s2
	s_load_dwordx8 s[84:91], s[36:37], s3
	v_mov_b32_e32 v149, 0
	v_mov_b32_e32 v150, 0
	v_mov_b32_e32 v151, 0
	v_mov_b32_e32 v148, 0
	v_dot4c_i32_i8_e32 v149, v152, v133
	v_dot4c_i32_i8_e32 v150, v156, v133
	v_dot4c_i32_i8_e32 v151, v160, v133
	v_dot4c_i32_i8_e32 v148, v164, v133
	v_dot4c_i32_i8_e32 v149, v153, v134
	v_dot4c_i32_i8_e32 v150, v157, v134
	v_dot4c_i32_i8_e32 v151, v161, v134
	v_dot4c_i32_i8_e32 v148, v165, v134
	v_dot4c_i32_i8_e32 v149, v154, v135
	v_dot4c_i32_i8_e32 v150, v158, v135
	v_dot4c_i32_i8_e32 v151, v162, v135
	v_dot4c_i32_i8_e32 v148, v166, v135
	v_dot4c_i32_i8_e32 v149, v155, v136
	v_dot4c_i32_i8_e32 v150, v159, v136
	v_dot4c_i32_i8_e32 v151, v163, v136
	v_dot4c_i32_i8_e32 v148, v167, v136
	s_nop 3
	v_cndmask_b32_e64 v143, v149, v150, s[0:1]
	v_cndmask_b32_e64 v144, v150, v149, s[0:1]
	v_cndmask_b32_e64 v145, v151, v148, s[0:1]
	v_cndmask_b32_e64 v146, v148, v151, s[0:1]
	s_nop 1
	v_add_u32_dpp v144, v143, v144 quad_perm:[1,0,3,2] row_mask:0xf bank_mask:0xf
	v_add_u32_dpp v146, v145, v146 quad_perm:[1,0,3,2] row_mask:0xf bank_mask:0xf
	s_nop 1
	v_cndmask_b32_e64 v143, v144, v146, s[6:7]
	v_cndmask_b32_e64 v145, v146, v144, s[6:7]
	s_nop 1
	v_add_u32_dpp v145, v143, v145 quad_perm:[2,3,0,1] row_mask:0xf bank_mask:0xf
	s_nop 1
	v_add_u32_dpp v145, v145, v145 row_ror:4 row_mask:0xf bank_mask:0xf
	s_nop 1
	v_add_u32_dpp v145, v145, v145 row_ror:8 row_mask:0xf bank_mask:0xf
	s_nop 1
	ds_bpermute_b32 v143, v126, v145
	s_waitcnt lgkmcnt(0)
	v_add_u32_e32 v145, v145, v143
	ds_bpermute_b32 v143, v127, v145
	s_waitcnt lgkmcnt(0)
	v_add_u32_e32 v145, v145, v143
	v_cvt_f32_i32_e32 v56, v145
	v_mul_f32_e32 v59, v140, v56
	v_mul_f32_e32 v59, v137, v59
	v_mul_f32_e32 v56, 0x3f3504f3, v59
	v_fma_f32 v143, |v56|, s66, v120
	v_fma_f32 v143, |v56|, v143, s67
	v_fma_f32 v143, |v56|, v143, s68
	v_fma_f32 v143, |v56|, v143, s69
	v_fma_f32 v143, |v56|, v143, s70
	v_fma_f32 v143, |v56|, v143, s71
	v_fma_f32 v143, |v56|, v143, |v56|
	v_mul_f32_e32 v144, 0xbfb8aa3b, v143
	v_fma_f32 v146, v143, s72, -v144
	v_rndne_f32_e32 v3, v144
	v_fmac_f32_e32 v146, 0xb2a5705f, v143
	v_sub_f32_e32 v144, v144, v3
	v_add_f32_e32 v144, v144, v146
	v_cvt_i32_f32_e32 v146, v3
	v_exp_f32_e32 v144, v144
	v_cmp_nlt_f32_e32 vcc, s73, v143
	v_ldexp_f32 v144, v144, v146
	s_nop 0
	v_cndmask_b32_e32 v144, 0, v144, vcc
	v_cmp_ngt_f32_e32 vcc, s74, v143
	s_nop 1
	v_cndmask_b32_e32 v143, v121, v144, vcc
	v_sub_f32_e32 v143, 1.0, v143
	v_mul_f32_e32 v168, v56, v56
	v_fmamk_f32 v169, v168, 0xba1345e1, v117
	v_fmaak_f32 v169, v168, v169, 0xbcdac9b8
	v_fmaak_f32 v169, v168, v169, 0x3de703be
	v_fmaak_f32 v169, v168, v169, 0xbec09330
	v_fmaak_f32 v168, v168, v169, 0x3e0375d0
	v_fma_f32 v168, |v56|, v168, |v56|
	v_cmp_nlt_f32_e64 vcc, |v56|, 1.0
	s_nop 1
	v_cndmask_b32_e32 v143, v168, v143, vcc
	v_bfi_b32 v146, s75, v143, v56
	v_mul_f32_e32 v145, 0.5, v59
	v_add_f32_e32 v146, 1.0, v146
	v_mul_f32_e32 v145, v145, v146
	v_mul_f32_e32 v144, v1, v145
	v_mul_f32_e32 v143, v141, v144
	s_nop 1
	v_readlane_b32 s40, v143, 0
	v_readlane_b32 s38, v143, 1
	v_readlane_b32 s42, v143, 2
	v_readlane_b32 s2, v143, 3
	s_nop 1
	v_add_f32_e32 v142, s40, v142
	v_add_f32_e32 v142, s38, v142
	v_add_f32_e32 v142, s42, v142
	v_add_f32_e32 v142, s2, v142
	v_cvt_f32_ubyte1_e32 v169, v12
	v_cvt_f32_ubyte0_e32 v168, v12
	v_pk_fma_f32 v[104:105], s[40:41], v[168:169], v[104:105] op_sel_hi:[0,1,1]
	v_cvt_f32_ubyte1_e32 v171, v20
	v_cvt_f32_ubyte0_e32 v170, v20
	v_pk_fma_f32 v[104:105], s[38:39], v[170:171], v[104:105] op_sel_hi:[0,1,1]
	v_cvt_f32_ubyte1_e32 v169, v24
	v_cvt_f32_ubyte0_e32 v168, v24
	v_pk_fma_f32 v[104:105], s[42:43], v[168:169], v[104:105] op_sel_hi:[0,1,1]
	v_cvt_f32_ubyte1_e32 v171, v28
	v_cvt_f32_ubyte0_e32 v170, v28
	v_pk_fma_f32 v[104:105], s[2:3], v[170:171], v[104:105] op_sel_hi:[0,1,1]
	v_cvt_f32_ubyte3_e32 v169, v12
	v_cvt_f32_ubyte2_e32 v168, v12
	v_pk_fma_f32 v[102:103], s[40:41], v[168:169], v[102:103] op_sel_hi:[0,1,1]
	v_cvt_f32_ubyte3_e32 v171, v20
	v_cvt_f32_ubyte2_e32 v170, v20
	v_pk_fma_f32 v[102:103], s[38:39], v[170:171], v[102:103] op_sel_hi:[0,1,1]
	v_cvt_f32_ubyte3_e32 v169, v24
	v_cvt_f32_ubyte2_e32 v168, v24
	v_pk_fma_f32 v[102:103], s[42:43], v[168:169], v[102:103] op_sel_hi:[0,1,1]
	v_cvt_f32_ubyte3_e32 v171, v28
	v_cvt_f32_ubyte2_e32 v170, v28
	v_pk_fma_f32 v[102:103], s[2:3], v[170:171], v[102:103] op_sel_hi:[0,1,1]
	v_cvt_f32_ubyte1_e32 v169, v13
	v_cvt_f32_ubyte0_e32 v168, v13
	v_pk_fma_f32 v[98:99], s[40:41], v[168:169], v[98:99] op_sel_hi:[0,1,1]
	v_cvt_f32_ubyte1_e32 v171, v21
	v_cvt_f32_ubyte0_e32 v170, v21
	v_pk_fma_f32 v[98:99], s[38:39], v[170:171], v[98:99] op_sel_hi:[0,1,1]
	v_cvt_f32_ubyte1_e32 v169, v25
	v_cvt_f32_ubyte0_e32 v168, v25
	v_pk_fma_f32 v[98:99], s[42:43], v[168:169], v[98:99] op_sel_hi:[0,1,1]
	v_cvt_f32_ubyte1_e32 v171, v29
	v_cvt_f32_ubyte0_e32 v170, v29
	v_pk_fma_f32 v[98:99], s[2:3], v[170:171], v[98:99] op_sel_hi:[0,1,1]
	v_cvt_f32_ubyte3_e32 v169, v13
	v_cvt_f32_ubyte2_e32 v168, v13
	v_pk_fma_f32 v[100:101], s[40:41], v[168:169], v[100:101] op_sel_hi:[0,1,1]
	v_cvt_f32_ubyte3_e32 v171, v21
	v_cvt_f32_ubyte2_e32 v170, v21
	v_pk_fma_f32 v[100:101], s[38:39], v[170:171], v[100:101] op_sel_hi:[0,1,1]
	v_cvt_f32_ubyte3_e32 v169, v25
	v_cvt_f32_ubyte2_e32 v168, v25
	v_pk_fma_f32 v[100:101], s[42:43], v[168:169], v[100:101] op_sel_hi:[0,1,1]
	v_cvt_f32_ubyte3_e32 v171, v29
	v_cvt_f32_ubyte2_e32 v170, v29
	v_pk_fma_f32 v[100:101], s[2:3], v[170:171], v[100:101] op_sel_hi:[0,1,1]
	v_cvt_f32_ubyte1_e32 v169, v14
	v_cvt_f32_ubyte0_e32 v168, v14
	v_pk_fma_f32 v[94:95], s[40:41], v[168:169], v[94:95] op_sel_hi:[0,1,1]
	v_cvt_f32_ubyte1_e32 v171, v22
	v_cvt_f32_ubyte0_e32 v170, v22
	v_pk_fma_f32 v[94:95], s[38:39], v[170:171], v[94:95] op_sel_hi:[0,1,1]
	v_cvt_f32_ubyte1_e32 v169, v26
	v_cvt_f32_ubyte0_e32 v168, v26
	v_pk_fma_f32 v[94:95], s[42:43], v[168:169], v[94:95] op_sel_hi:[0,1,1]
	v_cvt_f32_ubyte1_e32 v171, v30
	v_cvt_f32_ubyte0_e32 v170, v30
	v_pk_fma_f32 v[94:95], s[2:3], v[170:171], v[94:95] op_sel_hi:[0,1,1]
	v_cvt_f32_ubyte3_e32 v169, v14
	v_cvt_f32_ubyte2_e32 v168, v14
	v_pk_fma_f32 v[96:97], s[40:41], v[168:169], v[96:97] op_sel_hi:[0,1,1]
	v_cvt_f32_ubyte3_e32 v171, v22
	v_cvt_f32_ubyte2_e32 v170, v22
	v_pk_fma_f32 v[96:97], s[38:39], v[170:171], v[96:97] op_sel_hi:[0,1,1]
	v_cvt_f32_ubyte3_e32 v169, v26
	v_cvt_f32_ubyte2_e32 v168, v26
	v_pk_fma_f32 v[96:97], s[42:43], v[168:169], v[96:97] op_sel_hi:[0,1,1]
	v_cvt_f32_ubyte3_e32 v171, v30
	v_cvt_f32_ubyte2_e32 v170, v30
	v_pk_fma_f32 v[96:97], s[2:3], v[170:171], v[96:97] op_sel_hi:[0,1,1]
	v_cvt_f32_ubyte1_e32 v169, v15
	v_cvt_f32_ubyte0_e32 v168, v15
	v_pk_fma_f32 v[90:91], s[40:41], v[168:169], v[90:91] op_sel_hi:[0,1,1]
	v_cvt_f32_ubyte1_e32 v171, v23
	v_cvt_f32_ubyte0_e32 v170, v23
	v_pk_fma_f32 v[90:91], s[38:39], v[170:171], v[90:91] op_sel_hi:[0,1,1]
	v_cvt_f32_ubyte1_e32 v169, v27
	v_cvt_f32_ubyte0_e32 v168, v27
	v_pk_fma_f32 v[90:91], s[42:43], v[168:169], v[90:91] op_sel_hi:[0,1,1]
	v_cvt_f32_ubyte1_e32 v171, v31
	v_cvt_f32_ubyte0_e32 v170, v31
	v_pk_fma_f32 v[90:91], s[2:3], v[170:171], v[90:91] op_sel_hi:[0,1,1]
	v_cvt_f32_ubyte3_e32 v169, v15
	v_cvt_f32_ubyte2_e32 v168, v15
	v_pk_fma_f32 v[92:93], s[40:41], v[168:169], v[92:93] op_sel_hi:[0,1,1]
	v_cvt_f32_ubyte3_e32 v171, v23
	v_cvt_f32_ubyte2_e32 v170, v23
	v_pk_fma_f32 v[92:93], s[38:39], v[170:171], v[92:93] op_sel_hi:[0,1,1]
	v_cvt_f32_ubyte3_e32 v169, v27
	v_cvt_f32_ubyte2_e32 v168, v27
	v_pk_fma_f32 v[92:93], s[42:43], v[168:169], v[92:93] op_sel_hi:[0,1,1]
	v_cvt_f32_ubyte3_e32 v171, v31
	v_cvt_f32_ubyte2_e32 v170, v31
	v_pk_fma_f32 v[92:93], s[2:3], v[170:171], v[92:93] op_sel_hi:[0,1,1]
	s_waitcnt vmcnt(10) lgkmcnt(0)
	s_cmp_eq_u32 s80, s33
	s_cbranch_scc1 .Lxp_noswb
	s_lshl_b32 s2, s33, 12
	v_add_u32_e32 v249, s2, v248
	ds_write_b128 v249, v[90:93]
	ds_write_b128 v249, v[94:97] offset:1024
	ds_write_b128 v249, v[98:101] offset:2048
	ds_write_b128 v249, v[102:105] offset:3072
	v_cmp_eq_u32_e32 vcc, s33, v60
	s_nop 1
	v_cndmask_b32_e32 v243, v243, v142, vcc
	s_lshl_b32 s2, s80, 12
	v_add_u32_e32 v249, s2, v248
	ds_read_b128 v[90:93], v249
	ds_read_b128 v[94:97], v249 offset:1024
	ds_read_b128 v[98:101], v249 offset:2048
	ds_read_b128 v[102:105], v249 offset:3072
	s_nop 0
	v_readlane_b32 s2, v243, s80
	v_readlane_b32 s3, v244, s80
	s_nop 1
	v_mov_b32_e32 v142, s2
	v_mov_b32_e32 v137, s3
	s_cmp_eq_u32 s80, 0
	s_cbranch_scc1 .Lxp_lxqb0
	s_cmp_eq_u32 s80, 1
	s_cbranch_scc1 .Lxp_lxqb1
	s_cmp_eq_u32 s80, 2
	s_cbranch_scc1 .Lxp_lxqb2
	v_mov_b32_e32 v133, v236
	v_mov_b32_e32 v134, v237
	v_mov_b32_e32 v135, v238
	v_mov_b32_e32 v136, v239
	s_branch .Lxp_lxqbd

.Lxp_syncdc:
	s_and_b32 s84, s84, 0x3fff
	s_lshl_b32 s2, s84, 11
	v_lshl_add_u32 v249, v60, 4, s2
	global_load_dwordx4 v[152:155], v249, s[18:19]
	global_load_dwordx4 v[12:15], v249, s[20:21]
	s_lshl_b32 s2, s84, 2
	v_writelane_b32 v147, s2, 0
	v_writelane_b32 v1, s85, 0
	s_and_b32 s86, s86, 0x3fff
	s_lshl_b32 s2, s86, 11
	v_lshl_add_u32 v249, v60, 4, s2
	global_load_dwordx4 v[156:159], v249, s[18:19]
	global_load_dwordx4 v[20:23], v249, s[20:21]
	s_lshl_b32 s2, s86, 2
	v_writelane_b32 v147, s2, 1
	v_writelane_b32 v1, s87, 1
	s_and_b32 s88, s88, 0x3fff
	s_lshl_b32 s2, s88, 11
	v_lshl_add_u32 v249, v60, 4, s2
	global_load_dwordx4 v[160:163], v249, s[18:19]
	global_load_dwordx4 v[24:27], v249, s[20:21]
	s_lshl_b32 s2, s88, 2
	v_writelane_b32 v147, s2, 2
	v_writelane_b32 v1, s89, 2
	s_and_b32 s90, s90, 0x3fff
	s_lshl_b32 s2, s90, 11
	v_lshl_add_u32 v249, v60, 4, s2
	global_load_dwordx4 v[164:167], v249, s[18:19]
	global_load_dwordx4 v[28:31], v249, s[20:21]
	s_lshl_b32 s2, s90, 2
	v_writelane_b32 v147, s2, 3
	v_writelane_b32 v1, s91, 3
	global_load_dword v140, v147, s[44:45]
	global_load_dword v141, v147, s[46:47]
	s_add_i32 s3, s25, 3
	s_min_u32 s3, s3, 0x7f
	s_cmp_lt_u32 s3, 64
	s_cselect_b64 vcc, -1, 0
	s_nop 0
	v_cndmask_b32_e32 v249, v241, v240, vcc
	s_nop 1
	v_readlane_b32 s2, v249, s3
	s_and_b32 s3, s2, 31
	s_lshl_b32 s3, s3, 5
	s_bfe_u32 s94, s2, 0x20005
	s_lshl_b32 s2, s94, 11
	s_add_i32 s3, s3, s2
	s_load_dwordx8 s[84:91], s[36:37], s3
	v_mov_b32_e32 v149, 0
	v_mov_b32_e32 v150, 0
	v_mov_b32_e32 v151, 0
	v_mov_b32_e32 v148, 0
	v_dot4c_i32_i8_e32 v149, v72, v133
	v_dot4c_i32_i8_e32 v150, v76, v133
	v_dot4c_i32_i8_e32 v151, v80, v133
	v_dot4c_i32_i8_e32 v148, v84, v133
	v_dot4c_i32_i8_e32 v149, v73, v134
	v_dot4c_i32_i8_e32 v150, v77, v134
	v_dot4c_i32_i8_e32 v151, v81, v134
	v_dot4c_i32_i8_e32 v148, v85, v134
	v_dot4c_i32_i8_e32 v149, v74, v135
	v_dot4c_i32_i8_e32 v150, v78, v135
	v_dot4c_i32_i8_e32 v151, v82, v135
	v_dot4c_i32_i8_e32 v148, v86, v135
	v_dot4c_i32_i8_e32 v149, v75, v136
	v_dot4c_i32_i8_e32 v150, v79, v136
	v_dot4c_i32_i8_e32 v151, v83, v136
	v_dot4c_i32_i8_e32 v148, v87, v136
	s_nop 3
	v_cndmask_b32_e64 v143, v149, v150, s[0:1]
	v_cndmask_b32_e64 v144, v150, v149, s[0:1]
	v_cndmask_b32_e64 v145, v151, v148, s[0:1]
	v_cndmask_b32_e64 v146, v148, v151, s[0:1]
	s_nop 1
	v_add_u32_dpp v144, v143, v144 quad_perm:[1,0,3,2] row_mask:0xf bank_mask:0xf
	v_add_u32_dpp v146, v145, v146 quad_perm:[1,0,3,2] row_mask:0xf bank_mask:0xf
	s_nop 1
	v_cndmask_b32_e64 v143, v144, v146, s[6:7]
	v_cndmask_b32_e64 v145, v146, v144, s[6:7]
	s_nop 1
	v_add_u32_dpp v145, v143, v145 quad_perm:[2,3,0,1] row_mask:0xf bank_mask:0xf
	s_nop 1
	v_add_u32_dpp v145, v145, v145 row_ror:4 row_mask:0xf bank_mask:0xf
	s_nop 1
	v_add_u32_dpp v145, v145, v145 row_ror:8 row_mask:0xf bank_mask:0xf
	s_nop 1
	ds_bpermute_b32 v143, v126, v145
	s_waitcnt lgkmcnt(0)
	v_add_u32_e32 v145, v145, v143
	ds_bpermute_b32 v143, v127, v145
	s_waitcnt lgkmcnt(0)
	v_add_u32_e32 v145, v145, v143
	v_cvt_f32_i32_e32 v56, v145
	v_mul_f32_e32 v59, v88, v56
	v_mul_f32_e32 v59, v137, v59
	v_mul_f32_e32 v56, 0x3f3504f3, v59
	v_fma_f32 v143, |v56|, s66, v120
	v_fma_f32 v143, |v56|, v143, s67
	v_fma_f32 v143, |v56|, v143, s68
	v_fma_f32 v143, |v56|, v143, s69
	v_fma_f32 v143, |v56|, v143, s70
	v_fma_f32 v143, |v56|, v143, s71
	v_fma_f32 v143, |v56|, v143, |v56|
	v_mul_f32_e32 v144, 0xbfb8aa3b, v143
	v_fma_f32 v146, v143, s72, -v144
	v_rndne_f32_e32 v3, v144
	v_fmac_f32_e32 v146, 0xb2a5705f, v143
	v_sub_f32_e32 v144, v144, v3
	v_add_f32_e32 v144, v144, v146
	v_cvt_i32_f32_e32 v146, v3
	v_exp_f32_e32 v144, v144
	v_cmp_nlt_f32_e32 vcc, s73, v143
	v_ldexp_f32 v144, v144, v146
	s_nop 0
	v_cndmask_b32_e32 v144, 0, v144, vcc
	v_cmp_ngt_f32_e32 vcc, s74, v143
	s_nop 1
	v_cndmask_b32_e32 v143, v121, v144, vcc
	v_sub_f32_e32 v143, 1.0, v143
	v_mul_f32_e32 v168, v56, v56
	v_fmamk_f32 v169, v168, 0xba1345e1, v117
	v_fmaak_f32 v169, v168, v169, 0xbcdac9b8
	v_fmaak_f32 v169, v168, v169, 0x3de703be
	v_fmaak_f32 v169, v168, v169, 0xbec09330
	v_fmaak_f32 v168, v168, v169, 0x3e0375d0
	v_fma_f32 v168, |v56|, v168, |v56|
	v_cmp_nlt_f32_e64 vcc, |v56|, 1.0
	s_nop 1
	v_cndmask_b32_e32 v143, v168, v143, vcc
	v_bfi_b32 v146, s75, v143, v56
	v_mul_f32_e32 v145, 0.5, v59
	v_add_f32_e32 v146, 1.0, v146
	v_mul_f32_e32 v145, v145, v146
	v_mul_f32_e32 v144, v2, v145
	v_mul_f32_e32 v143, v89, v144
	s_nop 1
	v_readlane_b32 s40, v143, 0
	v_readlane_b32 s38, v143, 1
	v_readlane_b32 s42, v143, 2
	v_readlane_b32 s2, v143, 3
	s_nop 1
	v_add_f32_e32 v142, s40, v142
	v_add_f32_e32 v142, s38, v142
	v_add_f32_e32 v142, s42, v142
	v_add_f32_e32 v142, s2, v142
	v_cvt_f32_ubyte1_e32 v169, v64
	v_cvt_f32_ubyte0_e32 v168, v64
	v_pk_fma_f32 v[104:105], s[40:41], v[168:169], v[104:105] op_sel_hi:[0,1,1]
	v_cvt_f32_ubyte1_e32 v171, v68
	v_cvt_f32_ubyte0_e32 v170, v68
	v_pk_fma_f32 v[104:105], s[38:39], v[170:171], v[104:105] op_sel_hi:[0,1,1]
	v_cvt_f32_ubyte1_e32 v169, v4
	v_cvt_f32_ubyte0_e32 v168, v4
	v_pk_fma_f32 v[104:105], s[42:43], v[168:169], v[104:105] op_sel_hi:[0,1,1]
	v_cvt_f32_ubyte1_e32 v171, v128
	v_cvt_f32_ubyte0_e32 v170, v128
	v_pk_fma_f32 v[104:105], s[2:3], v[170:171], v[104:105] op_sel_hi:[0,1,1]
	v_cvt_f32_ubyte3_e32 v169, v64
	v_cvt_f32_ubyte2_e32 v168, v64
	v_pk_fma_f32 v[102:103], s[40:41], v[168:169], v[102:103] op_sel_hi:[0,1,1]
	v_cvt_f32_ubyte3_e32 v171, v68
	v_cvt_f32_ubyte2_e32 v170, v68
	v_pk_fma_f32 v[102:103], s[38:39], v[170:171], v[102:103] op_sel_hi:[0,1,1]
	v_cvt_f32_ubyte3_e32 v169, v4
	v_cvt_f32_ubyte2_e32 v168, v4
	v_pk_fma_f32 v[102:103], s[42:43], v[168:169], v[102:103] op_sel_hi:[0,1,1]
	v_cvt_f32_ubyte3_e32 v171, v128
	v_cvt_f32_ubyte2_e32 v170, v128
	v_pk_fma_f32 v[102:103], s[2:3], v[170:171], v[102:103] op_sel_hi:[0,1,1]
	v_cvt_f32_ubyte1_e32 v169, v65
	v_cvt_f32_ubyte0_e32 v168, v65
	v_pk_fma_f32 v[98:99], s[40:41], v[168:169], v[98:99] op_sel_hi:[0,1,1]
	v_cvt_f32_ubyte1_e32 v171, v69
	v_cvt_f32_ubyte0_e32 v170, v69
	v_pk_fma_f32 v[98:99], s[38:39], v[170:171], v[98:99] op_sel_hi:[0,1,1]
	v_cvt_f32_ubyte1_e32 v169, v5
	v_cvt_f32_ubyte0_e32 v168, v5
	v_pk_fma_f32 v[98:99], s[42:43], v[168:169], v[98:99] op_sel_hi:[0,1,1]
	v_cvt_f32_ubyte1_e32 v171, v129
	v_cvt_f32_ubyte0_e32 v170, v129
	v_pk_fma_f32 v[98:99], s[2:3], v[170:171], v[98:99] op_sel_hi:[0,1,1]
	v_cvt_f32_ubyte3_e32 v169, v65
	v_cvt_f32_ubyte2_e32 v168, v65
	v_pk_fma_f32 v[100:101], s[40:41], v[168:169], v[100:101] op_sel_hi:[0,1,1]
	v_cvt_f32_ubyte3_e32 v171, v69
	v_cvt_f32_ubyte2_e32 v170, v69
	v_pk_fma_f32 v[100:101], s[38:39], v[170:171], v[100:101] op_sel_hi:[0,1,1]
	v_cvt_f32_ubyte3_e32 v169, v5
	v_cvt_f32_ubyte2_e32 v168, v5
	v_pk_fma_f32 v[100:101], s[42:43], v[168:169], v[100:101] op_sel_hi:[0,1,1]
	v_cvt_f32_ubyte3_e32 v171, v129
	v_cvt_f32_ubyte2_e32 v170, v129
	v_pk_fma_f32 v[100:101], s[2:3], v[170:171], v[100:101] op_sel_hi:[0,1,1]
	v_cvt_f32_ubyte1_e32 v169, v66
	v_cvt_f32_ubyte0_e32 v168, v66
	v_pk_fma_f32 v[94:95], s[40:41], v[168:169], v[94:95] op_sel_hi:[0,1,1]
	v_cvt_f32_ubyte1_e32 v171, v70
	v_cvt_f32_ubyte0_e32 v170, v70
	v_pk_fma_f32 v[94:95], s[38:39], v[170:171], v[94:95] op_sel_hi:[0,1,1]
	v_cvt_f32_ubyte1_e32 v169, v6
	v_cvt_f32_ubyte0_e32 v168, v6
	v_pk_fma_f32 v[94:95], s[42:43], v[168:169], v[94:95] op_sel_hi:[0,1,1]
	v_cvt_f32_ubyte1_e32 v171, v130
	v_cvt_f32_ubyte0_e32 v170, v130
	v_pk_fma_f32 v[94:95], s[2:3], v[170:171], v[94:95] op_sel_hi:[0,1,1]
	v_cvt_f32_ubyte3_e32 v169, v66
	v_cvt_f32_ubyte2_e32 v168, v66
	v_pk_fma_f32 v[96:97], s[40:41], v[168:169], v[96:97] op_sel_hi:[0,1,1]
	v_cvt_f32_ubyte3_e32 v171, v70
	v_cvt_f32_ubyte2_e32 v170, v70
	v_pk_fma_f32 v[96:97], s[38:39], v[170:171], v[96:97] op_sel_hi:[0,1,1]
	v_cvt_f32_ubyte3_e32 v169, v6
	v_cvt_f32_ubyte2_e32 v168, v6
	v_pk_fma_f32 v[96:97], s[42:43], v[168:169], v[96:97] op_sel_hi:[0,1,1]
	v_cvt_f32_ubyte3_e32 v171, v130
	v_cvt_f32_ubyte2_e32 v170, v130
	v_pk_fma_f32 v[96:97], s[2:3], v[170:171], v[96:97] op_sel_hi:[0,1,1]
	v_cvt_f32_ubyte1_e32 v169, v67
	v_cvt_f32_ubyte0_e32 v168, v67
	v_pk_fma_f32 v[90:91], s[40:41], v[168:169], v[90:91] op_sel_hi:[0,1,1]
	v_cvt_f32_ubyte1_e32 v171, v71
	v_cvt_f32_ubyte0_e32 v170, v71
	v_pk_fma_f32 v[90:91], s[38:39], v[170:171], v[90:91] op_sel_hi:[0,1,1]
	v_cvt_f32_ubyte1_e32 v169, v7
	v_cvt_f32_ubyte0_e32 v168, v7
	v_pk_fma_f32 v[90:91], s[42:43], v[168:169], v[90:91] op_sel_hi:[0,1,1]
	v_cvt_f32_ubyte1_e32 v171, v131
	v_cvt_f32_ubyte0_e32 v170, v131
	v_pk_fma_f32 v[90:91], s[2:3], v[170:171], v[90:91] op_sel_hi:[0,1,1]
	v_cvt_f32_ubyte3_e32 v169, v67
	v_cvt_f32_ubyte2_e32 v168, v67
	v_pk_fma_f32 v[92:93], s[40:41], v[168:169], v[92:93] op_sel_hi:[0,1,1]
	v_cvt_f32_ubyte3_e32 v171, v71
	v_cvt_f32_ubyte2_e32 v170, v71
	v_pk_fma_f32 v[92:93], s[38:39], v[170:171], v[92:93] op_sel_hi:[0,1,1]
	v_cvt_f32_ubyte3_e32 v169, v7
	v_cvt_f32_ubyte2_e32 v168, v7
	v_pk_fma_f32 v[92:93], s[42:43], v[168:169], v[92:93] op_sel_hi:[0,1,1]
	v_cvt_f32_ubyte3_e32 v171, v131
	v_cvt_f32_ubyte2_e32 v170, v131
	v_pk_fma_f32 v[92:93], s[2:3], v[170:171], v[92:93] op_sel_hi:[0,1,1]
	s_waitcnt vmcnt(10) lgkmcnt(0)
	s_cmp_eq_u32 s80, s33
	s_cbranch_scc1 .Lxp_noswc
	s_lshl_b32 s2, s33, 12
	v_add_u32_e32 v249, s2, v248
	ds_write_b128 v249, v[90:93]
	ds_write_b128 v249, v[94:97] offset:1024
	ds_write_b128 v249, v[98:101] offset:2048
	ds_write_b128 v249, v[102:105] offset:3072
	v_cmp_eq_u32_e32 vcc, s33, v60
	s_nop 1
	v_cndmask_b32_e32 v243, v243, v142, vcc
	s_lshl_b32 s2, s80, 12
	v_add_u32_e32 v249, s2, v248
	ds_read_b128 v[90:93], v249
	ds_read_b128 v[94:97], v249 offset:1024
	ds_read_b128 v[98:101], v249 offset:2048
	ds_read_b128 v[102:105], v249 offset:3072
	s_nop 0
	v_readlane_b32 s2, v243, s80
	v_readlane_b32 s3, v244, s80
	s_nop 1
	v_mov_b32_e32 v142, s2
	v_mov_b32_e32 v137, s3
	s_cmp_eq_u32 s80, 0
	s_cbranch_scc1 .Lxp_lxqc0
	s_cmp_eq_u32 s80, 1
	s_cbranch_scc1 .Lxp_lxqc1
	s_cmp_eq_u32 s80, 2
	s_cbranch_scc1 .Lxp_lxqc2
	v_mov_b32_e32 v133, v236
	v_mov_b32_e32 v134, v237
	v_mov_b32_e32 v135, v238
	v_mov_b32_e32 v136, v239
	s_branch .Lxp_lxqcd

.Lxp_noswc:
	s_mov_b32 s80, s81
	s_mov_b32 s81, s94
	s_add_i32 s25, s25, 1
	s_cmp_lt_u32 s25, 126
	s_cbranch_scc1 .Lxp_unit
	s_cmp_eq_u32 s82, 1
	s_cbranch_scc0 .Lxp_fold
	s_lshl_b32 s2, s25, 7
	s_add_i32 s2, s2, s97
	s_and_b32 s2, s2, 0x3fff
	v_mov_b32_e32 v245, s2
	s_mov_b64 exec, 1
	global_store_dword v[246:247], v245, off
	s_mov_b64 exec, -1
	s_sleep 3
	s_branch .Lxp_syncdd
